# v18 cache hints + conv GLU staging pipelined two iterations deep (re-test under the new cache regime)
# baseline (speedup 1.0000x reference)
; #define LAS __attribute__((address_space(3)))
; __device__ __forceinline__ float bflo(unsigned w) { return __uint_as_float(w << 16); }
; __device__ __forceinline__ float bfhi(unsigned w) { return __uint_as_float(w & 0xffff0000u); }
; __device__ __forceinline__ void conv_unit(LAS unsigned char* lds, int u, const bf16* PROJ, const float* conv_w, const float* conv_b, const float* ln_w, const float* ln_b, bf16* MIX, int tid, const WsRef& wsr) {
;     ...
;     for (int it = tid; it < 62 * 64; it += 512) { const int r = it >> 6, cc = it & 63; const int t = t0 - 15 + r;
;         f32x4 u0 = (f32x4){0.f, 0.f, 0.f, 0.f}, u1 = u0;
;         if (t >= 0 && t < SEQ) { const bf16* pr = PROJ + (rowb + t) * INC + 2048 + cc * 8; const u32x4 a = *(const u32x4*)pr, g = *(const u32x4*)(pr + 512);
; #pragma unroll
;             for (int e = 0; e < 4; ++e) { const float a0 = bflo(a[e]), a1 = bfhi(a[e]), g0 = bflo(g[e]), g1 = bfhi(g[e]);
;                 const float v0 = a0 * __builtin_amdgcn_rcpf(1.f + __expf(-g0)), v1 = a1 * __builtin_amdgcn_rcpf(1.f + __expf(-g1));
;                 if (e < 2) { u0[2 * e] = v0; u0[2 * e + 1] = v1; } else { u1[2 * e - 4] = v0; u1[2 * e - 3] = v1; } } }
;         *(LAS f32x4*)(U + r * 512 + cc * 8) = u0; *(LAS f32x4*)(U + r * 512 + cc * 8 + 4) = u1; }
.Lcp_full:
	v_mov_b32_e32 v104, v84
	s_mov_b64 s[10:11], exec
	v_cmp_gt_u32_e32 vcc, s24, v104
	s_and_b64 s[14:15], s[10:11], vcc
	s_mov_b64 exec, s[14:15]
	v_or_b32_e32 v2, s8, v104
	v_mov_b64_e32 v[0:1], s[6:7]
	v_mad_u64_u32 v[0:1], s[30:31], v2, s25, v[0:1]
	v_mad_i32_i24 v1, s9, v218, v1
	v_lshl_add_u64 v[4:5], v[0:1], 0, v[8:9]
	v_lshl_add_u64 v[0:1], v[4:5], 0, s[4:5]
	v_add_co_u32_e32 v4, vcc, 0x1000, v4
	global_load_dwordx4 v[150:153], v[0:1], off offset:1024 nt
	s_nop 0
	v_addc_co_u32_e32 v5, vcc, 0, v5, vcc
	global_load_dwordx4 v[154:157], v[4:5], off nt
	s_mov_b64 exec, -1
	v_add_u32_e32 v104, 8, v84
	v_add_u32_e32 v106, 0x200, v88
	v_cmp_lt_u32_e32 vcc, s26, v106
	s_andn2_b64 s[10:11], exec, vcc
	v_cmp_gt_u32_e32 vcc, s24, v104
	s_and_b64 s[14:15], s[10:11], vcc
	s_mov_b64 exec, s[14:15]
	v_or_b32_e32 v2, s8, v104
	v_mov_b64_e32 v[0:1], s[6:7]
	v_mad_u64_u32 v[0:1], s[30:31], v2, s25, v[0:1]
	v_mad_i32_i24 v1, s9, v218, v1
	v_lshl_add_u64 v[4:5], v[0:1], 0, v[8:9]
	v_lshl_add_u64 v[0:1], v[4:5], 0, s[4:5]
	v_add_co_u32_e32 v4, vcc, 0x1000, v4
	global_load_dwordx4 v[158:161], v[0:1], off offset:1024 nt
	s_nop 0
	v_addc_co_u32_e32 v5, vcc, 0, v5, vcc
	global_load_dwordx4 v[162:165], v[4:5], off nt
	s_mov_b64 exec, -1
	s_waitcnt vmcnt(0)
	v_add_u32_e32 v104, 16, v84
	v_add_u32_e32 v106, 0x400, v88
	v_cmp_lt_u32_e32 vcc, s26, v106
	s_andn2_b64 s[10:11], exec, vcc
	v_cmp_gt_u32_e32 vcc, s24, v104
	s_and_b64 s[14:15], s[10:11], vcc
	s_mov_b64 exec, s[14:15]
	v_or_b32_e32 v2, s8, v104
	v_mov_b64_e32 v[0:1], s[6:7]
	v_mad_u64_u32 v[0:1], s[30:31], v2, s25, v[0:1]
	v_mad_i32_i24 v1, s9, v218, v1
	v_lshl_add_u64 v[4:5], v[0:1], 0, v[8:9]
	v_lshl_add_u64 v[0:1], v[4:5], 0, s[4:5]
	v_add_co_u32_e32 v4, vcc, 0x1000, v4
	global_load_dwordx4 v[166:169], v[0:1], off offset:1024 nt
	s_nop 0
	v_addc_co_u32_e32 v5, vcc, 0, v5, vcc
	global_load_dwordx4 v[170:173], v[4:5], off nt
	s_mov_b64 exec, -1
	v_add_u32_e32 v104, 24, v84
	v_add_u32_e32 v106, 0x600, v88
	v_cmp_lt_u32_e32 vcc, s26, v106
	s_andn2_b64 s[10:11], exec, vcc
	v_cmp_gt_u32_e32 vcc, s24, v104
	s_and_b64 s[14:15], s[10:11], vcc
	s_mov_b64 exec, s[14:15]
	v_or_b32_e32 v2, s8, v104
	v_mov_b64_e32 v[0:1], s[6:7]
	v_mad_u64_u32 v[0:1], s[30:31], v2, s25, v[0:1]
	v_mad_i32_i24 v1, s9, v218, v1
	v_lshl_add_u64 v[4:5], v[0:1], 0, v[8:9]
	v_lshl_add_u64 v[0:1], v[4:5], 0, s[4:5]
	v_add_co_u32_e32 v4, vcc, 0x1000, v4
	global_load_dwordx4 v[174:177], v[0:1], off offset:1024 nt
	s_nop 0
	v_addc_co_u32_e32 v5, vcc, 0, v5, vcc
	global_load_dwordx4 v[178:181], v[4:5], off nt
	s_mov_b64 exec, -1
	v_mov_b32_e32 v104, v84
	s_mov_b64 s[10:11], exec
	v_cmp_gt_u32_e32 vcc, s24, v104
	s_and_b64 s[14:15], s[10:11], vcc
	v_mov_b32_e32 v0, 0
	v_mov_b32_e32 v1, 0
	v_mov_b32_e32 v2, 0
	v_mov_b32_e32 v3, 0
	v_mov_b32_e32 v4, 0
	v_mov_b32_e32 v5, 0
	v_mov_b32_e32 v6, 0
	v_mov_b32_e32 v7, 0
	s_mov_b64 exec, s[14:15]
	v_mov_b32_e32 v0, v150
	v_mov_b32_e32 v1, v151
	v_mov_b32_e32 v2, v152
	v_mov_b32_e32 v3, v153
	v_mov_b32_e32 v4, v154
	v_mov_b32_e32 v5, v155
	v_mov_b32_e32 v6, v156
	v_mov_b32_e32 v7, v157
	v_and_b32_e32 v90, 0xffff0000, v0
	v_lshlrev_b32_e32 v92, 16, v0
	v_lshlrev_b32_e32 v94, 16, v1
	v_lshlrev_b32_e32 v142, 16, v4
	v_and_b32_e32 v143, 0xffff0000, v4
	v_and_b32_e32 v4, 0xffff0000, v1
	v_lshlrev_b32_e32 v0, 16, v5
	v_and_b32_e32 v1, 0xffff0000, v5
	v_and_b32_e32 v5, 0xffff0000, v2
	v_lshlrev_b32_e32 v96, 16, v2
	v_lshlrev_b32_e32 v144, 16, v6
	v_and_b32_e32 v145, 0xffff0000, v6
	v_lshlrev_b32_e32 v6, 16, v3
	v_and_b32_e32 v98, 0xffff0000, v3
	v_lshlrev_b32_e32 v2, 16, v7
	v_and_b32_e32 v3, 0xffff0000, v7
	v_mul_f32_e32 v7, 0xbfb8aa3b, v90
	v_mul_f32_e32 v90, 0xbfb8aa3b, v92
	v_mul_f32_e32 v4, 0xbfb8aa3b, v4
	v_mul_f32_e32 v92, 0xbfb8aa3b, v94
	v_mul_f32_e32 v5, 0xbfb8aa3b, v5
	v_mul_f32_e32 v94, 0xbfb8aa3b, v96
	v_mul_f32_e32 v6, 0xbfb8aa3b, v6
	v_mul_f32_e32 v96, 0xbfb8aa3b, v98
	v_exp_f32_e32 v7, v7
	v_exp_f32_e32 v90, v90
	v_exp_f32_e32 v4, v4
	v_exp_f32_e32 v92, v92
	v_exp_f32_e32 v5, v5
	v_exp_f32_e32 v94, v94
	v_exp_f32_e32 v6, v6
	v_exp_f32_e32 v96, v96
	v_add_f32_e32 v7, 1.0, v7
	v_add_f32_e32 v90, 1.0, v90
	v_add_f32_e32 v98, 1.0, v4
	v_add_f32_e32 v92, 1.0, v92
	v_add_f32_e32 v100, 1.0, v5
	v_add_f32_e32 v94, 1.0, v94
	v_add_f32_e32 v102, 1.0, v6
	v_add_f32_e32 v96, 1.0, v96
	v_rcp_f32_e32 v5, v7
	v_rcp_f32_e32 v4, v90
	v_rcp_f32_e32 v7, v98
	v_rcp_f32_e32 v6, v92
	v_rcp_f32_e32 v147, v100
	v_rcp_f32_e32 v146, v94
	v_rcp_f32_e32 v148, v102
	v_rcp_f32_e32 v149, v96
	v_pk_mul_f32 v[4:5], v[4:5], v[142:143]
	v_pk_mul_f32 v[6:7], v[6:7], v[0:1]
	v_pk_mul_f32 v[0:1], v[146:147], v[144:145]
	v_pk_mul_f32 v[2:3], v[148:149], v[2:3]
	s_mov_b64 exec, s[10:11]
	v_mov_b32_e32 v108, v86
	ds_write_b128 v108, v[4:7]
	ds_write_b128 v108, v[0:3] offset:16
	s_mov_b64 exec, -1
	v_add_u32_e32 v104, 8, v84
	v_add_u32_e32 v106, 0x200, v88
	v_cmp_lt_u32_e32 vcc, s26, v106
	s_andn2_b64 s[10:11], exec, vcc
	v_cmp_gt_u32_e32 vcc, s24, v104
	s_and_b64 s[14:15], s[10:11], vcc
	v_mov_b32_e32 v0, 0
	v_mov_b32_e32 v1, 0
	v_mov_b32_e32 v2, 0
	v_mov_b32_e32 v3, 0
	v_mov_b32_e32 v4, 0
	v_mov_b32_e32 v5, 0
	v_mov_b32_e32 v6, 0
	v_mov_b32_e32 v7, 0
	s_mov_b64 exec, s[14:15]
	v_mov_b32_e32 v0, v158
	v_mov_b32_e32 v1, v159
	v_mov_b32_e32 v2, v160
	v_mov_b32_e32 v3, v161
	v_mov_b32_e32 v4, v162
	v_mov_b32_e32 v5, v163
	v_mov_b32_e32 v6, v164
	v_mov_b32_e32 v7, v165
	v_and_b32_e32 v90, 0xffff0000, v0
	v_lshlrev_b32_e32 v92, 16, v0
	v_lshlrev_b32_e32 v94, 16, v1
	v_lshlrev_b32_e32 v142, 16, v4
	v_and_b32_e32 v143, 0xffff0000, v4
	v_and_b32_e32 v4, 0xffff0000, v1
	v_lshlrev_b32_e32 v0, 16, v5
	v_and_b32_e32 v1, 0xffff0000, v5
; #define LAS __attribute__((address_space(3)))
; __device__ __forceinline__ float bflo(unsigned w) { return __uint_as_float(w << 16); }
; __device__ __forceinline__ float bfhi(unsigned w) { return __uint_as_float(w & 0xffff0000u); }
; __device__ __forceinline__ void conv_unit(LAS unsigned char* lds, int u, const bf16* PROJ, const float* conv_w, const float* conv_b, const float* ln_w, const float* ln_b, bf16* MIX, int tid, const WsRef& wsr) {
;     ...
;     for (int it = tid; it < 62 * 64; it += 512) { const int r = it >> 6, cc = it & 63; const int t = t0 - 15 + r;
;         f32x4 u0 = (f32x4){0.f, 0.f, 0.f, 0.f}, u1 = u0;
;         if (t >= 0 && t < SEQ) { const bf16* pr = PROJ + (rowb + t) * INC + 2048 + cc * 8; const u32x4 a = *(const u32x4*)pr, g = *(const u32x4*)(pr + 512);
; #pragma unroll
;             for (int e = 0; e < 4; ++e) { const float a0 = bflo(a[e]), a1 = bfhi(a[e]), g0 = bflo(g[e]), g1 = bfhi(g[e]);
;                 const float v0 = a0 * __builtin_amdgcn_rcpf(1.f + __expf(-g0)), v1 = a1 * __builtin_amdgcn_rcpf(1.f + __expf(-g1));
;                 if (e < 2) { u0[2 * e] = v0; u0[2 * e + 1] = v1; } else { u1[2 * e - 4] = v0; u1[2 * e - 3] = v1; } } }
;         *(LAS f32x4*)(U + r * 512 + cc * 8) = u0; *(LAS f32x4*)(U + r * 512 + cc * 8 + 4) = u1; }
	v_and_b32_e32 v5, 0xffff0000, v2
	v_lshlrev_b32_e32 v96, 16, v2
	v_lshlrev_b32_e32 v144, 16, v6
	v_and_b32_e32 v145, 0xffff0000, v6
	v_lshlrev_b32_e32 v6, 16, v3
	v_and_b32_e32 v98, 0xffff0000, v3
	v_lshlrev_b32_e32 v2, 16, v7
	v_and_b32_e32 v3, 0xffff0000, v7
	v_mul_f32_e32 v7, 0xbfb8aa3b, v90
	v_mul_f32_e32 v90, 0xbfb8aa3b, v92
	v_mul_f32_e32 v4, 0xbfb8aa3b, v4
	v_mul_f32_e32 v92, 0xbfb8aa3b, v94
	v_mul_f32_e32 v5, 0xbfb8aa3b, v5
	v_mul_f32_e32 v94, 0xbfb8aa3b, v96
	v_mul_f32_e32 v6, 0xbfb8aa3b, v6
	v_mul_f32_e32 v96, 0xbfb8aa3b, v98
	v_exp_f32_e32 v7, v7
	v_exp_f32_e32 v90, v90
	v_exp_f32_e32 v4, v4
	v_exp_f32_e32 v92, v92
	v_exp_f32_e32 v5, v5
	v_exp_f32_e32 v94, v94
	v_exp_f32_e32 v6, v6
	v_exp_f32_e32 v96, v96
	v_add_f32_e32 v7, 1.0, v7
	v_add_f32_e32 v90, 1.0, v90
	v_add_f32_e32 v98, 1.0, v4
	v_add_f32_e32 v92, 1.0, v92
	v_add_f32_e32 v100, 1.0, v5
	v_add_f32_e32 v94, 1.0, v94
	v_add_f32_e32 v102, 1.0, v6
	v_add_f32_e32 v96, 1.0, v96
	v_rcp_f32_e32 v5, v7
	v_rcp_f32_e32 v4, v90
	v_rcp_f32_e32 v7, v98
	v_rcp_f32_e32 v6, v92
	v_rcp_f32_e32 v147, v100
	v_rcp_f32_e32 v146, v94
	v_rcp_f32_e32 v148, v102
	v_rcp_f32_e32 v149, v96
	v_pk_mul_f32 v[4:5], v[4:5], v[142:143]
	v_pk_mul_f32 v[6:7], v[6:7], v[0:1]
	v_pk_mul_f32 v[0:1], v[146:147], v[144:145]
	v_pk_mul_f32 v[2:3], v[148:149], v[2:3]
	s_mov_b64 exec, s[10:11]
	v_add_u32_e32 v108, 0x4000, v86
	ds_write_b128 v108, v[4:7]
	ds_write_b128 v108, v[0:3] offset:16
	s_mov_b64 exec, -1
	s_waitcnt vmcnt(0)
	v_add_u32_e32 v104, 32, v84
	v_add_u32_e32 v106, 0x800, v88
	v_cmp_lt_u32_e32 vcc, s26, v106
	s_andn2_b64 s[10:11], exec, vcc
	v_cmp_gt_u32_e32 vcc, s24, v104
	s_and_b64 s[14:15], s[10:11], vcc
	s_mov_b64 exec, s[14:15]
	v_or_b32_e32 v2, s8, v104
	v_mov_b64_e32 v[0:1], s[6:7]
	v_mad_u64_u32 v[0:1], s[30:31], v2, s25, v[0:1]
	v_mad_i32_i24 v1, s9, v218, v1
	v_lshl_add_u64 v[4:5], v[0:1], 0, v[8:9]
	v_lshl_add_u64 v[0:1], v[4:5], 0, s[4:5]
	v_add_co_u32_e32 v4, vcc, 0x1000, v4
	global_load_dwordx4 v[150:153], v[0:1], off offset:1024 nt
	s_nop 0
	v_addc_co_u32_e32 v5, vcc, 0, v5, vcc
	global_load_dwordx4 v[154:157], v[4:5], off nt
	s_mov_b64 exec, -1
	v_add_u32_e32 v104, 40, v84
	v_add_u32_e32 v106, 0xa00, v88
	v_cmp_lt_u32_e32 vcc, s26, v106
	s_andn2_b64 s[10:11], exec, vcc
	v_cmp_gt_u32_e32 vcc, s24, v104
	s_and_b64 s[14:15], s[10:11], vcc
	s_mov_b64 exec, s[14:15]
	v_or_b32_e32 v2, s8, v104
	v_mov_b64_e32 v[0:1], s[6:7]
	v_mad_u64_u32 v[0:1], s[30:31], v2, s25, v[0:1]
	v_mad_i32_i24 v1, s9, v218, v1
	v_lshl_add_u64 v[4:5], v[0:1], 0, v[8:9]
	v_lshl_add_u64 v[0:1], v[4:5], 0, s[4:5]
	v_add_co_u32_e32 v4, vcc, 0x1000, v4
	global_load_dwordx4 v[158:161], v[0:1], off offset:1024 nt
	s_nop 0
	v_addc_co_u32_e32 v5, vcc, 0, v5, vcc
	global_load_dwordx4 v[162:165], v[4:5], off nt
	s_mov_b64 exec, -1
	v_add_u32_e32 v104, 16, v84
	v_add_u32_e32 v106, 0x400, v88
	v_cmp_lt_u32_e32 vcc, s26, v106
	s_andn2_b64 s[10:11], exec, vcc
	v_cmp_gt_u32_e32 vcc, s24, v104
	s_and_b64 s[14:15], s[10:11], vcc
	v_mov_b32_e32 v0, 0
	v_mov_b32_e32 v1, 0
	v_mov_b32_e32 v2, 0
	v_mov_b32_e32 v3, 0
	v_mov_b32_e32 v4, 0
	v_mov_b32_e32 v5, 0
	v_mov_b32_e32 v6, 0
	v_mov_b32_e32 v7, 0
	s_mov_b64 exec, s[14:15]
	v_mov_b32_e32 v0, v166
	v_mov_b32_e32 v1, v167
	v_mov_b32_e32 v2, v168
	v_mov_b32_e32 v3, v169
	v_mov_b32_e32 v4, v170
	v_mov_b32_e32 v5, v171
	v_mov_b32_e32 v6, v172
	v_mov_b32_e32 v7, v173
	v_and_b32_e32 v90, 0xffff0000, v0
	v_lshlrev_b32_e32 v92, 16, v0
	v_lshlrev_b32_e32 v94, 16, v1
	v_lshlrev_b32_e32 v142, 16, v4
	v_and_b32_e32 v143, 0xffff0000, v4
	v_and_b32_e32 v4, 0xffff0000, v1
	v_lshlrev_b32_e32 v0, 16, v5
	v_and_b32_e32 v1, 0xffff0000, v5
	v_and_b32_e32 v5, 0xffff0000, v2
	v_lshlrev_b32_e32 v96, 16, v2
	v_lshlrev_b32_e32 v144, 16, v6
	v_and_b32_e32 v145, 0xffff0000, v6
	v_lshlrev_b32_e32 v6, 16, v3
	v_and_b32_e32 v98, 0xffff0000, v3
	v_lshlrev_b32_e32 v2, 16, v7
	v_and_b32_e32 v3, 0xffff0000, v7
	v_mul_f32_e32 v7, 0xbfb8aa3b, v90
	v_mul_f32_e32 v90, 0xbfb8aa3b, v92
	v_mul_f32_e32 v4, 0xbfb8aa3b, v4
	v_mul_f32_e32 v92, 0xbfb8aa3b, v94
	v_mul_f32_e32 v5, 0xbfb8aa3b, v5
	v_mul_f32_e32 v94, 0xbfb8aa3b, v96
	v_mul_f32_e32 v6, 0xbfb8aa3b, v6
	v_mul_f32_e32 v96, 0xbfb8aa3b, v98
	v_exp_f32_e32 v7, v7
	v_exp_f32_e32 v90, v90
	v_exp_f32_e32 v4, v4
	v_exp_f32_e32 v92, v92
	v_exp_f32_e32 v5, v5
	v_exp_f32_e32 v94, v94
	v_exp_f32_e32 v6, v6
	v_exp_f32_e32 v96, v96
	v_add_f32_e32 v7, 1.0, v7
	v_add_f32_e32 v90, 1.0, v90
	v_add_f32_e32 v98, 1.0, v4
	v_add_f32_e32 v92, 1.0, v92
	v_add_f32_e32 v100, 1.0, v5
	v_add_f32_e32 v94, 1.0, v94
	v_add_f32_e32 v102, 1.0, v6
	v_add_f32_e32 v96, 1.0, v96
	v_rcp_f32_e32 v5, v7
	v_rcp_f32_e32 v4, v90
	v_rcp_f32_e32 v7, v98
	v_rcp_f32_e32 v6, v92
	v_rcp_f32_e32 v147, v100
	v_rcp_f32_e32 v146, v94
	v_rcp_f32_e32 v148, v102
	v_rcp_f32_e32 v149, v96
	v_pk_mul_f32 v[4:5], v[4:5], v[142:143]
	v_pk_mul_f32 v[6:7], v[6:7], v[0:1]
	v_pk_mul_f32 v[0:1], v[146:147], v[144:145]
	v_pk_mul_f32 v[2:3], v[148:149], v[2:3]
	s_mov_b64 exec, s[10:11]
	v_add_u32_e32 v108, 0x8000, v86
	ds_write_b128 v108, v[4:7]
	ds_write_b128 v108, v[0:3] offset:16
	s_mov_b64 exec, -1
	v_add_u32_e32 v104, 24, v84
	v_add_u32_e32 v106, 0x600, v88
	v_cmp_lt_u32_e32 vcc, s26, v106
	s_andn2_b64 s[10:11], exec, vcc
	v_cmp_gt_u32_e32 vcc, s24, v104
	s_and_b64 s[14:15], s[10:11], vcc
	v_mov_b32_e32 v0, 0
	v_mov_b32_e32 v1, 0
	v_mov_b32_e32 v2, 0
	v_mov_b32_e32 v3, 0
	v_mov_b32_e32 v4, 0
	v_mov_b32_e32 v5, 0
	v_mov_b32_e32 v6, 0
	v_mov_b32_e32 v7, 0
	s_mov_b64 exec, s[14:15]
	v_mov_b32_e32 v0, v174
	v_mov_b32_e32 v1, v175
	v_mov_b32_e32 v2, v176
	v_mov_b32_e32 v3, v177
	v_mov_b32_e32 v4, v178
	v_mov_b32_e32 v5, v179
	v_mov_b32_e32 v6, v180
; #define LAS __attribute__((address_space(3)))
; __device__ __forceinline__ float bflo(unsigned w) { return __uint_as_float(w << 16); }
; __device__ __forceinline__ float bfhi(unsigned w) { return __uint_as_float(w & 0xffff0000u); }
; __device__ __forceinline__ void conv_unit(LAS unsigned char* lds, int u, const bf16* PROJ, const float* conv_w, const float* conv_b, const float* ln_w, const float* ln_b, bf16* MIX, int tid, const WsRef& wsr) {
;     ...
;     for (int it = tid; it < 62 * 64; it += 512) { const int r = it >> 6, cc = it & 63; const int t = t0 - 15 + r;
;         f32x4 u0 = (f32x4){0.f, 0.f, 0.f, 0.f}, u1 = u0;
;         if (t >= 0 && t < SEQ) { const bf16* pr = PROJ + (rowb + t) * INC + 2048 + cc * 8; const u32x4 a = *(const u32x4*)pr, g = *(const u32x4*)(pr + 512);
; #pragma unroll
;             for (int e = 0; e < 4; ++e) { const float a0 = bflo(a[e]), a1 = bfhi(a[e]), g0 = bflo(g[e]), g1 = bfhi(g[e]);
;                 const float v0 = a0 * __builtin_amdgcn_rcpf(1.f + __expf(-g0)), v1 = a1 * __builtin_amdgcn_rcpf(1.f + __expf(-g1));
;                 if (e < 2) { u0[2 * e] = v0; u0[2 * e + 1] = v1; } else { u1[2 * e - 4] = v0; u1[2 * e - 3] = v1; } } }
;         *(LAS f32x4*)(U + r * 512 + cc * 8) = u0; *(LAS f32x4*)(U + r * 512 + cc * 8 + 4) = u1; }
	v_mov_b32_e32 v7, v181
	v_and_b32_e32 v90, 0xffff0000, v0
	v_lshlrev_b32_e32 v92, 16, v0
	v_lshlrev_b32_e32 v94, 16, v1
	v_lshlrev_b32_e32 v142, 16, v4
	v_and_b32_e32 v143, 0xffff0000, v4
	v_and_b32_e32 v4, 0xffff0000, v1
	v_lshlrev_b32_e32 v0, 16, v5
	v_and_b32_e32 v1, 0xffff0000, v5
	v_and_b32_e32 v5, 0xffff0000, v2
	v_lshlrev_b32_e32 v96, 16, v2
	v_lshlrev_b32_e32 v144, 16, v6
	v_and_b32_e32 v145, 0xffff0000, v6
	v_lshlrev_b32_e32 v6, 16, v3
	v_and_b32_e32 v98, 0xffff0000, v3
	v_lshlrev_b32_e32 v2, 16, v7
	v_and_b32_e32 v3, 0xffff0000, v7
	v_mul_f32_e32 v7, 0xbfb8aa3b, v90
	v_mul_f32_e32 v90, 0xbfb8aa3b, v92
	v_mul_f32_e32 v4, 0xbfb8aa3b, v4
	v_mul_f32_e32 v92, 0xbfb8aa3b, v94
	v_mul_f32_e32 v5, 0xbfb8aa3b, v5
	v_mul_f32_e32 v94, 0xbfb8aa3b, v96
	v_mul_f32_e32 v6, 0xbfb8aa3b, v6
	v_mul_f32_e32 v96, 0xbfb8aa3b, v98
	v_exp_f32_e32 v7, v7
	v_exp_f32_e32 v90, v90
	v_exp_f32_e32 v4, v4
	v_exp_f32_e32 v92, v92
	v_exp_f32_e32 v5, v5
	v_exp_f32_e32 v94, v94
	v_exp_f32_e32 v6, v6
	v_exp_f32_e32 v96, v96
	v_add_f32_e32 v7, 1.0, v7
	v_add_f32_e32 v90, 1.0, v90
	v_add_f32_e32 v98, 1.0, v4
	v_add_f32_e32 v92, 1.0, v92
	v_add_f32_e32 v100, 1.0, v5
	v_add_f32_e32 v94, 1.0, v94
	v_add_f32_e32 v102, 1.0, v6
	v_add_f32_e32 v96, 1.0, v96
	v_rcp_f32_e32 v5, v7
	v_rcp_f32_e32 v4, v90
	v_rcp_f32_e32 v7, v98
	v_rcp_f32_e32 v6, v92
	v_rcp_f32_e32 v147, v100
	v_rcp_f32_e32 v146, v94
	v_rcp_f32_e32 v148, v102
	v_rcp_f32_e32 v149, v96
	v_pk_mul_f32 v[4:5], v[4:5], v[142:143]
	v_pk_mul_f32 v[6:7], v[6:7], v[0:1]
	v_pk_mul_f32 v[0:1], v[146:147], v[144:145]
	v_pk_mul_f32 v[2:3], v[148:149], v[2:3]
	s_mov_b64 exec, s[10:11]
	v_add_u32_e32 v108, 0xc000, v86
	ds_write_b128 v108, v[4:7]
	ds_write_b128 v108, v[0:3] offset:16
	s_mov_b64 exec, -1
	s_waitcnt vmcnt(0)
	v_add_u32_e32 v104, 48, v84
	v_add_u32_e32 v106, 0xc00, v88
	v_cmp_lt_u32_e32 vcc, s26, v106
	s_andn2_b64 s[10:11], exec, vcc
	v_cmp_gt_u32_e32 vcc, s24, v104
	s_and_b64 s[14:15], s[10:11], vcc
	s_mov_b64 exec, s[14:15]
	v_or_b32_e32 v2, s8, v104
	v_mov_b64_e32 v[0:1], s[6:7]
	v_mad_u64_u32 v[0:1], s[30:31], v2, s25, v[0:1]
	v_mad_i32_i24 v1, s9, v218, v1
	v_lshl_add_u64 v[4:5], v[0:1], 0, v[8:9]
	v_lshl_add_u64 v[0:1], v[4:5], 0, s[4:5]
	v_add_co_u32_e32 v4, vcc, 0x1000, v4
	global_load_dwordx4 v[166:169], v[0:1], off offset:1024 nt
	s_nop 0
	v_addc_co_u32_e32 v5, vcc, 0, v5, vcc
	global_load_dwordx4 v[170:173], v[4:5], off nt
	s_mov_b64 exec, -1
	v_add_u32_e32 v104, 56, v84
	v_add_u32_e32 v106, 0xe00, v88
	v_cmp_lt_u32_e32 vcc, s26, v106
	s_andn2_b64 s[10:11], exec, vcc
	v_cmp_gt_u32_e32 vcc, s24, v104
	s_and_b64 s[14:15], s[10:11], vcc
	s_mov_b64 exec, s[14:15]
	v_or_b32_e32 v2, s8, v104
	v_mov_b64_e32 v[0:1], s[6:7]
	v_mad_u64_u32 v[0:1], s[30:31], v2, s25, v[0:1]
	v_mad_i32_i24 v1, s9, v218, v1
	v_lshl_add_u64 v[4:5], v[0:1], 0, v[8:9]
	v_lshl_add_u64 v[0:1], v[4:5], 0, s[4:5]
	v_add_co_u32_e32 v4, vcc, 0x1000, v4
	global_load_dwordx4 v[174:177], v[0:1], off offset:1024 nt
	s_nop 0
	v_addc_co_u32_e32 v5, vcc, 0, v5, vcc
	global_load_dwordx4 v[178:181], v[4:5], off nt
	s_mov_b64 exec, -1
	v_add_u32_e32 v104, 32, v84
	v_add_u32_e32 v106, 0x800, v88
	v_cmp_lt_u32_e32 vcc, s26, v106
	s_andn2_b64 s[10:11], exec, vcc
	v_cmp_gt_u32_e32 vcc, s24, v104
	s_and_b64 s[14:15], s[10:11], vcc
	v_mov_b32_e32 v0, 0
	v_mov_b32_e32 v1, 0
	v_mov_b32_e32 v2, 0
	v_mov_b32_e32 v3, 0
	v_mov_b32_e32 v4, 0
	v_mov_b32_e32 v5, 0
	v_mov_b32_e32 v6, 0
	v_mov_b32_e32 v7, 0
	s_mov_b64 exec, s[14:15]
	v_mov_b32_e32 v0, v150
	v_mov_b32_e32 v1, v151
	v_mov_b32_e32 v2, v152
	v_mov_b32_e32 v3, v153
	v_mov_b32_e32 v4, v154
	v_mov_b32_e32 v5, v155
	v_mov_b32_e32 v6, v156
	v_mov_b32_e32 v7, v157
	v_and_b32_e32 v90, 0xffff0000, v0
	v_lshlrev_b32_e32 v92, 16, v0
	v_lshlrev_b32_e32 v94, 16, v1
	v_lshlrev_b32_e32 v142, 16, v4
	v_and_b32_e32 v143, 0xffff0000, v4
	v_and_b32_e32 v4, 0xffff0000, v1
	v_lshlrev_b32_e32 v0, 16, v5
	v_and_b32_e32 v1, 0xffff0000, v5
	v_and_b32_e32 v5, 0xffff0000, v2
	v_lshlrev_b32_e32 v96, 16, v2
	v_lshlrev_b32_e32 v144, 16, v6
	v_and_b32_e32 v145, 0xffff0000, v6
	v_lshlrev_b32_e32 v6, 16, v3
	v_and_b32_e32 v98, 0xffff0000, v3
	v_lshlrev_b32_e32 v2, 16, v7
	v_and_b32_e32 v3, 0xffff0000, v7
	v_mul_f32_e32 v7, 0xbfb8aa3b, v90
	v_mul_f32_e32 v90, 0xbfb8aa3b, v92
	v_mul_f32_e32 v4, 0xbfb8aa3b, v4
	v_mul_f32_e32 v92, 0xbfb8aa3b, v94
	v_mul_f32_e32 v5, 0xbfb8aa3b, v5
	v_mul_f32_e32 v94, 0xbfb8aa3b, v96
	v_mul_f32_e32 v6, 0xbfb8aa3b, v6
	v_mul_f32_e32 v96, 0xbfb8aa3b, v98
	v_exp_f32_e32 v7, v7
	v_exp_f32_e32 v90, v90
	v_exp_f32_e32 v4, v4
	v_exp_f32_e32 v92, v92
	v_exp_f32_e32 v5, v5
	v_exp_f32_e32 v94, v94
	v_exp_f32_e32 v6, v6
	v_exp_f32_e32 v96, v96
	v_add_f32_e32 v7, 1.0, v7
	v_add_f32_e32 v90, 1.0, v90
	v_add_f32_e32 v98, 1.0, v4
	v_add_f32_e32 v92, 1.0, v92
	v_add_f32_e32 v100, 1.0, v5
	v_add_f32_e32 v94, 1.0, v94
	v_add_f32_e32 v102, 1.0, v6
	v_add_f32_e32 v96, 1.0, v96
	v_rcp_f32_e32 v5, v7
	v_rcp_f32_e32 v4, v90
	v_rcp_f32_e32 v7, v98
	v_rcp_f32_e32 v6, v92
	v_rcp_f32_e32 v147, v100
	v_rcp_f32_e32 v146, v94
	v_rcp_f32_e32 v148, v102
	v_rcp_f32_e32 v149, v96
	v_pk_mul_f32 v[4:5], v[4:5], v[142:143]
	v_pk_mul_f32 v[6:7], v[6:7], v[0:1]
	v_pk_mul_f32 v[0:1], v[146:147], v[144:145]
	v_pk_mul_f32 v[2:3], v[148:149], v[2:3]
	s_mov_b64 exec, s[10:11]
	v_add_u32_e32 v108, 0x10000, v86
	ds_write_b128 v108, v[4:7]
	ds_write_b128 v108, v[0:3] offset:16
	s_mov_b64 exec, -1
	v_add_u32_e32 v104, 40, v84
	v_add_u32_e32 v106, 0xa00, v88
	v_cmp_lt_u32_e32 vcc, s26, v106
	s_andn2_b64 s[10:11], exec, vcc
	v_cmp_gt_u32_e32 vcc, s24, v104
	s_and_b64 s[14:15], s[10:11], vcc
	v_mov_b32_e32 v0, 0
	v_mov_b32_e32 v1, 0
	v_mov_b32_e32 v2, 0
; #define LAS __attribute__((address_space(3)))
; __device__ __forceinline__ float bflo(unsigned w) { return __uint_as_float(w << 16); }
; __device__ __forceinline__ float bfhi(unsigned w) { return __uint_as_float(w & 0xffff0000u); }
; __device__ __forceinline__ void conv_unit(LAS unsigned char* lds, int u, const bf16* PROJ, const float* conv_w, const float* conv_b, const float* ln_w, const float* ln_b, bf16* MIX, int tid, const WsRef& wsr) {
;     ...
;     for (int it = tid; it < 62 * 64; it += 512) { const int r = it >> 6, cc = it & 63; const int t = t0 - 15 + r;
;         f32x4 u0 = (f32x4){0.f, 0.f, 0.f, 0.f}, u1 = u0;
;         if (t >= 0 && t < SEQ) { const bf16* pr = PROJ + (rowb + t) * INC + 2048 + cc * 8; const u32x4 a = *(const u32x4*)pr, g = *(const u32x4*)(pr + 512);
; #pragma unroll
;             for (int e = 0; e < 4; ++e) { const float a0 = bflo(a[e]), a1 = bfhi(a[e]), g0 = bflo(g[e]), g1 = bfhi(g[e]);
;                 const float v0 = a0 * __builtin_amdgcn_rcpf(1.f + __expf(-g0)), v1 = a1 * __builtin_amdgcn_rcpf(1.f + __expf(-g1));
;                 if (e < 2) { u0[2 * e] = v0; u0[2 * e + 1] = v1; } else { u1[2 * e - 4] = v0; u1[2 * e - 3] = v1; } } }
;         *(LAS f32x4*)(U + r * 512 + cc * 8) = u0; *(LAS f32x4*)(U + r * 512 + cc * 8 + 4) = u1; }
	v_mov_b32_e32 v3, 0
	v_mov_b32_e32 v4, 0
	v_mov_b32_e32 v5, 0
	v_mov_b32_e32 v6, 0
	v_mov_b32_e32 v7, 0
	s_mov_b64 exec, s[14:15]
	v_mov_b32_e32 v0, v158
	v_mov_b32_e32 v1, v159
	v_mov_b32_e32 v2, v160
	v_mov_b32_e32 v3, v161
	v_mov_b32_e32 v4, v162
	v_mov_b32_e32 v5, v163
	v_mov_b32_e32 v6, v164
	v_mov_b32_e32 v7, v165
	v_and_b32_e32 v90, 0xffff0000, v0
	v_lshlrev_b32_e32 v92, 16, v0
	v_lshlrev_b32_e32 v94, 16, v1
	v_lshlrev_b32_e32 v142, 16, v4
	v_and_b32_e32 v143, 0xffff0000, v4
	v_and_b32_e32 v4, 0xffff0000, v1
	v_lshlrev_b32_e32 v0, 16, v5
	v_and_b32_e32 v1, 0xffff0000, v5
	v_and_b32_e32 v5, 0xffff0000, v2
	v_lshlrev_b32_e32 v96, 16, v2
	v_lshlrev_b32_e32 v144, 16, v6
	v_and_b32_e32 v145, 0xffff0000, v6
	v_lshlrev_b32_e32 v6, 16, v3
	v_and_b32_e32 v98, 0xffff0000, v3
	v_lshlrev_b32_e32 v2, 16, v7
	v_and_b32_e32 v3, 0xffff0000, v7
	v_mul_f32_e32 v7, 0xbfb8aa3b, v90
	v_mul_f32_e32 v90, 0xbfb8aa3b, v92
	v_mul_f32_e32 v4, 0xbfb8aa3b, v4
	v_mul_f32_e32 v92, 0xbfb8aa3b, v94
	v_mul_f32_e32 v5, 0xbfb8aa3b, v5
	v_mul_f32_e32 v94, 0xbfb8aa3b, v96
	v_mul_f32_e32 v6, 0xbfb8aa3b, v6
	v_mul_f32_e32 v96, 0xbfb8aa3b, v98
	v_exp_f32_e32 v7, v7
	v_exp_f32_e32 v90, v90
	v_exp_f32_e32 v4, v4
	v_exp_f32_e32 v92, v92
	v_exp_f32_e32 v5, v5
	v_exp_f32_e32 v94, v94
	v_exp_f32_e32 v6, v6
	v_exp_f32_e32 v96, v96
	v_add_f32_e32 v7, 1.0, v7
	v_add_f32_e32 v90, 1.0, v90
	v_add_f32_e32 v98, 1.0, v4
	v_add_f32_e32 v92, 1.0, v92
	v_add_f32_e32 v100, 1.0, v5
	v_add_f32_e32 v94, 1.0, v94
	v_add_f32_e32 v102, 1.0, v6
	v_add_f32_e32 v96, 1.0, v96
	v_rcp_f32_e32 v5, v7
	v_rcp_f32_e32 v4, v90
	v_rcp_f32_e32 v7, v98
	v_rcp_f32_e32 v6, v92
	v_rcp_f32_e32 v147, v100
	v_rcp_f32_e32 v146, v94
	v_rcp_f32_e32 v148, v102
	v_rcp_f32_e32 v149, v96
	v_pk_mul_f32 v[4:5], v[4:5], v[142:143]
	v_pk_mul_f32 v[6:7], v[6:7], v[0:1]
	v_pk_mul_f32 v[0:1], v[146:147], v[144:145]
	v_pk_mul_f32 v[2:3], v[148:149], v[2:3]
	s_mov_b64 exec, s[10:11]
	v_add_u32_e32 v108, 0x14000, v86
	ds_write_b128 v108, v[4:7]
	ds_write_b128 v108, v[0:3] offset:16
	s_mov_b64 exec, -1
	s_waitcnt vmcnt(0)
	v_add_u32_e32 v104, 48, v84
	v_add_u32_e32 v106, 0xc00, v88
	v_cmp_lt_u32_e32 vcc, s26, v106
	s_andn2_b64 s[10:11], exec, vcc
	v_cmp_gt_u32_e32 vcc, s24, v104
	s_and_b64 s[14:15], s[10:11], vcc
	v_mov_b32_e32 v0, 0
	v_mov_b32_e32 v1, 0
	v_mov_b32_e32 v2, 0
	v_mov_b32_e32 v3, 0
	v_mov_b32_e32 v4, 0
	v_mov_b32_e32 v5, 0
	v_mov_b32_e32 v6, 0
	v_mov_b32_e32 v7, 0
	s_mov_b64 exec, s[14:15]
	v_mov_b32_e32 v0, v166
	v_mov_b32_e32 v1, v167
	v_mov_b32_e32 v2, v168
	v_mov_b32_e32 v3, v169
	v_mov_b32_e32 v4, v170
	v_mov_b32_e32 v5, v171
	v_mov_b32_e32 v6, v172
	v_mov_b32_e32 v7, v173
	v_and_b32_e32 v90, 0xffff0000, v0
	v_lshlrev_b32_e32 v92, 16, v0
	v_lshlrev_b32_e32 v94, 16, v1
	v_lshlrev_b32_e32 v142, 16, v4
	v_and_b32_e32 v143, 0xffff0000, v4
	v_and_b32_e32 v4, 0xffff0000, v1
	v_lshlrev_b32_e32 v0, 16, v5
	v_and_b32_e32 v1, 0xffff0000, v5
	v_and_b32_e32 v5, 0xffff0000, v2
	v_lshlrev_b32_e32 v96, 16, v2
	v_lshlrev_b32_e32 v144, 16, v6
	v_and_b32_e32 v145, 0xffff0000, v6
	v_lshlrev_b32_e32 v6, 16, v3
	v_and_b32_e32 v98, 0xffff0000, v3
	v_lshlrev_b32_e32 v2, 16, v7
	v_and_b32_e32 v3, 0xffff0000, v7
	v_mul_f32_e32 v7, 0xbfb8aa3b, v90
	v_mul_f32_e32 v90, 0xbfb8aa3b, v92
	v_mul_f32_e32 v4, 0xbfb8aa3b, v4
	v_mul_f32_e32 v92, 0xbfb8aa3b, v94
	v_mul_f32_e32 v5, 0xbfb8aa3b, v5
	v_mul_f32_e32 v94, 0xbfb8aa3b, v96
	v_mul_f32_e32 v6, 0xbfb8aa3b, v6
	v_mul_f32_e32 v96, 0xbfb8aa3b, v98
	v_exp_f32_e32 v7, v7
	v_exp_f32_e32 v90, v90
	v_exp_f32_e32 v4, v4
	v_exp_f32_e32 v92, v92
	v_exp_f32_e32 v5, v5
	v_exp_f32_e32 v94, v94
	v_exp_f32_e32 v6, v6
	v_exp_f32_e32 v96, v96
	v_add_f32_e32 v7, 1.0, v7
	v_add_f32_e32 v90, 1.0, v90
	v_add_f32_e32 v98, 1.0, v4
	v_add_f32_e32 v92, 1.0, v92
	v_add_f32_e32 v100, 1.0, v5
	v_add_f32_e32 v94, 1.0, v94
	v_add_f32_e32 v102, 1.0, v6
	v_add_f32_e32 v96, 1.0, v96
	v_rcp_f32_e32 v5, v7
	v_rcp_f32_e32 v4, v90
	v_rcp_f32_e32 v7, v98
	v_rcp_f32_e32 v6, v92
	v_rcp_f32_e32 v147, v100
	v_rcp_f32_e32 v146, v94
	v_rcp_f32_e32 v148, v102
	v_rcp_f32_e32 v149, v96
	v_pk_mul_f32 v[4:5], v[4:5], v[142:143]
	v_pk_mul_f32 v[6:7], v[6:7], v[0:1]
	v_pk_mul_f32 v[0:1], v[146:147], v[144:145]
	v_pk_mul_f32 v[2:3], v[148:149], v[2:3]
	s_mov_b64 exec, s[10:11]
	v_add_u32_e32 v108, 0x18000, v86
	ds_write_b128 v108, v[4:7]
	ds_write_b128 v108, v[0:3] offset:16
	s_mov_b64 exec, -1
	v_add_u32_e32 v104, 56, v84
	v_add_u32_e32 v106, 0xe00, v88
	v_cmp_lt_u32_e32 vcc, s26, v106
	s_andn2_b64 s[10:11], exec, vcc
	v_cmp_gt_u32_e32 vcc, s24, v104
	s_and_b64 s[14:15], s[10:11], vcc
	v_mov_b32_e32 v0, 0
	v_mov_b32_e32 v1, 0
	v_mov_b32_e32 v2, 0
	v_mov_b32_e32 v3, 0
	v_mov_b32_e32 v4, 0
	v_mov_b32_e32 v5, 0
	v_mov_b32_e32 v6, 0
	v_mov_b32_e32 v7, 0
	s_mov_b64 exec, s[14:15]
	v_mov_b32_e32 v0, v174
	v_mov_b32_e32 v1, v175
	v_mov_b32_e32 v2, v176
	v_mov_b32_e32 v3, v177
	v_mov_b32_e32 v4, v178
	v_mov_b32_e32 v5, v179
	v_mov_b32_e32 v6, v180
	v_mov_b32_e32 v7, v181
	v_and_b32_e32 v90, 0xffff0000, v0
	v_lshlrev_b32_e32 v92, 16, v0
	v_lshlrev_b32_e32 v94, 16, v1
	v_lshlrev_b32_e32 v142, 16, v4
	v_and_b32_e32 v143, 0xffff0000, v4
	v_and_b32_e32 v4, 0xffff0000, v1
	v_lshlrev_b32_e32 v0, 16, v5
	v_and_b32_e32 v1, 0xffff0000, v5
	v_and_b32_e32 v5, 0xffff0000, v2
	v_lshlrev_b32_e32 v96, 16, v2
	v_lshlrev_b32_e32 v144, 16, v6
	v_and_b32_e32 v145, 0xffff0000, v6
	v_lshlrev_b32_e32 v6, 16, v3
	v_and_b32_e32 v98, 0xffff0000, v3
	v_lshlrev_b32_e32 v2, 16, v7
	v_and_b32_e32 v3, 0xffff0000, v7
	v_mul_f32_e32 v7, 0xbfb8aa3b, v90
	v_mul_f32_e32 v90, 0xbfb8aa3b, v92
	v_mul_f32_e32 v4, 0xbfb8aa3b, v4
	v_mul_f32_e32 v92, 0xbfb8aa3b, v94
	v_mul_f32_e32 v5, 0xbfb8aa3b, v5
	v_mul_f32_e32 v94, 0xbfb8aa3b, v96
	v_mul_f32_e32 v6, 0xbfb8aa3b, v6
	v_mul_f32_e32 v96, 0xbfb8aa3b, v98
	v_exp_f32_e32 v7, v7
	v_exp_f32_e32 v90, v90
	v_exp_f32_e32 v4, v4
	v_exp_f32_e32 v92, v92
	v_exp_f32_e32 v5, v5
	v_exp_f32_e32 v94, v94
	v_exp_f32_e32 v6, v6
	v_exp_f32_e32 v96, v96
	v_add_f32_e32 v7, 1.0, v7
	v_add_f32_e32 v90, 1.0, v90
	v_add_f32_e32 v98, 1.0, v4
	v_add_f32_e32 v92, 1.0, v92
	v_add_f32_e32 v100, 1.0, v5
	v_add_f32_e32 v94, 1.0, v94
	v_add_f32_e32 v102, 1.0, v6
	v_add_f32_e32 v96, 1.0, v96
	v_rcp_f32_e32 v5, v7
	v_rcp_f32_e32 v4, v90
	v_rcp_f32_e32 v7, v98
	v_rcp_f32_e32 v6, v92
	v_rcp_f32_e32 v147, v100
	v_rcp_f32_e32 v146, v94
	v_rcp_f32_e32 v148, v102
	v_rcp_f32_e32 v149, v96
	v_pk_mul_f32 v[4:5], v[4:5], v[142:143]
	v_pk_mul_f32 v[6:7], v[6:7], v[0:1]
	v_pk_mul_f32 v[0:1], v[146:147], v[144:145]
	v_pk_mul_f32 v[2:3], v[148:149], v[2:3]
	s_mov_b64 exec, s[10:11]
	v_add_u32_e32 v108, 0x1c000, v86
	ds_write_b128 v108, v[4:7]
	ds_write_b128 v108, v[0:3] offset:16
	s_mov_b64 exec, -1
	s_mov_b64 s[10:11], 0
	s_branch .LBB0_220
